# EpiResid second half: residual fragment loads as 16-byte loads as well
# speedup vs baseline: 1.0220x; 1.0015x over previous
; __device__ __forceinline__ unsigned cvt_pk_bf16(float lo, float hi) { unsigned r; asm volatile("v_cvt_pk_bf16_f32 %0, %1, %2" : "=v"(r) : "v"(lo), "v"(hi)); return r; }
;     __device__ __forceinline__ void operator()(f32x4 (&acc)[2][2][4][2], const Unit& u, int wr, int wc, int fr, int fq) const {
;     ...
;             for (int m = 0; m < 4; ++m) { const size_t off = (size_t)(u.pm * BM + ai * HALF + wr * 64 + m * 16 + fr) * ldc + col0;
; #pragma unroll
;                 for (int bj = 0; bj < 2; ++bj)
; #pragma unroll
;                     for (int n = 0; n < 2; ++n) old[m][bj][n] = *(const unsigned long long*)(xb + off + bj * HALF + n * 16); }
; #pragma unroll
;             for (int m = 0; m < 4; ++m) { const int row = u.pm * BM + ai * HALF + wr * 64 + m * 16 + fr; const size_t off = (size_t)row * ldc + col0; float sq = 0.f;
; #pragma unroll
;                 for (int bj = 0; bj < 2; ++bj)
; #pragma unroll
;                     for (int n = 0; n < 2; ++n) { const unsigned long long b = old[m][bj][n];
;                         const unsigned blo = (unsigned)b, bhi = (unsigned)(b >> 32);
;                         f32x4 v; v[0] = __builtin_bit_cast(float, blo << 16); v[1] = __builtin_bit_cast(float, blo & 0xffff0000u); v[2] = __builtin_bit_cast(float, bhi << 16); v[3] = __builtin_bit_cast(float, bhi & 0xffff0000u);
;                         v = v + acc[ai][bj][m][n];
;                         sq += (v[0] * v[0] + v[1] * v[1]) + (v[2] * v[2] + v[3] * v[3]);
;                         *(unsigned long long*)(xb + off + bj * HALF + n * 16) = (unsigned long long)cvt_pk_bf16(v[0], v[1]) | ((unsigned long long)cvt_pk_bf16(v[2], v[3]) << 32); }
;                 sq += __shfl_xor(sq, 16); sq += __shfl_xor(sq, 32);
;                 if (fq == 0) ssp[(size_t)row * 16 + 4 * u.pn + wc] = sq; }
.LBB0_1047:
	s_or_b64 exec, exec, s[80:81]
	v_add_u32_e32 v96, 0x80, v140
	v_ashrrev_i32_e32 v97, 31, v96
	v_lshlrev_b64 v[102:103], 11, v[96:97]
	s_waitcnt lgkmcnt(0)
	v_lshl_add_u64 v[66:67], v[138:139], 0, v[102:103]
	v_lshl_add_u64 v[66:67], v[66:67], 0, v[200:201]
	global_load_dwordx4 v[104:107], v[66:67], off
	global_load_dwordx4 v[98:101], v[66:67], off offset:256
	v_add_u32_e32 v84, 0x90, v140
	v_ashrrev_i32_e32 v85, 31, v84
	v_lshlrev_b64 v[66:67], 11, v[84:85]
	v_add_u32_e32 v70, 0xa0, v140
	v_lshl_add_u64 v[66:67], v[138:139], 0, v[66:67]
	v_ashrrev_i32_e32 v71, 31, v70
	v_lshl_add_u64 v[66:67], v[66:67], 0, v[200:201]
	global_load_dwordx4 v[88:91], v[66:67], off
	global_load_dwordx4 v[92:95], v[66:67], off offset:256
	v_lshlrev_b64 v[66:67], 11, v[70:71]
	v_lshl_add_u64 v[66:67], v[138:139], 0, v[66:67]
	v_lshl_add_u64 v[66:67], v[66:67], 0, v[200:201]
	global_load_dwordx4 v[72:75], v[66:67], off
	global_load_dwordx4 v[76:79], v[66:67], off offset:256
	v_add_u32_e32 v66, 0xb0, v140
	v_ashrrev_i32_e32 v67, 31, v66
	v_lshlrev_b64 v[68:69], 11, v[66:67]
	v_lshl_add_u64 v[68:69], v[138:139], 0, v[68:69]
	v_lshl_add_u64 v[68:69], v[68:69], 0, v[200:201]
	global_load_dwordx4 v[80:83], v[68:69], off
	s_nop 0
	global_load_dwordx4 v[202:205], v[68:69], off offset:256
	s_waitcnt vmcnt(0)
	v_permlane16_swap_b32_e32 v104, v106
	v_permlane16_swap_b32_e32 v105, v107
	v_permlane16_swap_b32_e32 v98, v100
	v_permlane16_swap_b32_e32 v99, v101
	v_permlane16_swap_b32_e32 v88, v90
	v_permlane16_swap_b32_e32 v89, v91
	v_permlane16_swap_b32_e32 v92, v94
	v_permlane16_swap_b32_e32 v93, v95
	v_permlane16_swap_b32_e32 v72, v74
	v_permlane16_swap_b32_e32 v73, v75
	v_permlane16_swap_b32_e32 v76, v78
	v_permlane16_swap_b32_e32 v77, v79
	v_permlane16_swap_b32_e32 v80, v82
	v_permlane16_swap_b32_e32 v81, v83
	v_permlane16_swap_b32_e32 v202, v204
	v_permlane16_swap_b32_e32 v203, v205
	v_mov_b32_e32 v86, v72
	v_mov_b32_e32 v87, v73
	v_mov_b32_e32 v72, v202
	v_mov_b32_e32 v73, v203
	v_mov_b32_e32 v68, v204
	v_mov_b32_e32 v69, v205
	v_mov_b32_e32 v209, v100
	v_mov_b32_e32 v100, v98
	v_mov_b32_e32 v98, v209
	v_mov_b32_e32 v208, v101
	v_mov_b32_e32 v101, v99
	v_mov_b32_e32 v99, v208
	v_mov_b32_e32 v207, v94
	v_mov_b32_e32 v94, v88
	v_mov_b32_e32 v88, v207
	v_mov_b32_e32 v206, v95
	v_mov_b32_e32 v95, v89
	v_mov_b32_e32 v89, v206
	v_mov_b32_e32 v199, v92
	v_mov_b32_e32 v92, v90
	v_mov_b32_e32 v90, v199
	v_mov_b32_e32 v198, v93
	v_mov_b32_e32 v93, v91
	v_mov_b32_e32 v91, v198
	v_mov_b32_e32 v197, v82
	v_mov_b32_e32 v82, v74
	v_mov_b32_e32 v74, v78
	v_mov_b32_e32 v78, v76
	v_mov_b32_e32 v76, v197
	v_mov_b32_e32 v196, v83
	v_mov_b32_e32 v83, v75
	v_mov_b32_e32 v75, v79
	v_mov_b32_e32 v79, v77
	v_mov_b32_e32 v77, v196
	v_lshlrev_b32_e32 v108, 16, v104
	v_and_b32_e32 v109, 0xffff0000, v104
	v_lshlrev_b32_e32 v104, 16, v105
	v_and_b32_e32 v105, 0xffff0000, v105
	v_pk_add_f32 v[64:65], v[64:65], v[104:105]
	v_pk_add_f32 v[62:63], v[62:63], v[108:109]
	v_mul_f32_e32 v105, v65, v65
	v_mul_f32_e32 v104, v63, v63
	v_fmac_f32_e32 v104, v62, v62
	v_fmac_f32_e32 v105, v64, v64
	v_add_f32_e32 v108, v104, v105
	v_cvt_pk_bf16_f32 v104, v62, v63
	v_cvt_pk_bf16_f32 v105, v64, v65
	s_waitcnt vmcnt(14)
	v_lshlrev_b32_e32 v64, 16, v106
	v_and_b32_e32 v65, 0xffff0000, v106
	v_lshl_add_u64 v[62:63], s[42:43], 0, v[102:103]
	v_pk_add_f32 v[58:59], v[58:59], v[64:65]
	v_lshl_add_u64 v[62:63], v[136:137], 1, v[62:63]
	v_lshlrev_b32_e32 v102, 16, v107
	v_and_b32_e32 v103, 0xffff0000, v107
	v_mul_f32_e32 v64, v59, v59
	v_lshl_add_u64 v[62:63], v[62:63], 0, v[200:201]
	v_mov_b32_e32 v192, v104
	v_mov_b32_e32 v193, v105
	v_pk_add_f32 v[60:61], v[60:61], v[102:103]
	v_fmac_f32_e32 v64, v58, v58
	v_cvt_pk_bf16_f32 v58, v58, v59
	v_cvt_pk_bf16_f32 v59, v60, v61
	v_mul_f32_e32 v65, v61, v61
	v_mov_b32_e32 v194, v58
	v_mov_b32_e32 v195, v59
	s_nop 1
	v_permlane16_swap_b32_e32 v192, v194
	v_permlane16_swap_b32_e32 v193, v195
	global_store_dwordx4 v[62:63], v[192:195], off
	s_waitcnt vmcnt(14)
	v_lshlrev_b32_e32 v58, 16, v100
	v_and_b32_e32 v59, 0xffff0000, v100
	v_fmac_f32_e32 v65, v60, v60
	v_lshlrev_b32_e32 v60, 16, v101
	v_and_b32_e32 v61, 0xffff0000, v101
	v_pk_add_f32 v[54:55], v[54:55], v[58:59]
	v_pk_add_f32 v[56:57], v[56:57], v[60:61]
	v_mul_f32_e32 v58, v55, v55
	v_fmac_f32_e32 v58, v54, v54
	v_mul_f32_e32 v59, v57, v57
	v_cvt_pk_bf16_f32 v54, v54, v55
	v_cvt_pk_bf16_f32 v55, v56, v57
	v_fmac_f32_e32 v59, v56, v56
	v_mov_b32_e32 v196, v54
	v_mov_b32_e32 v197, v55
	s_waitcnt vmcnt(13)
	v_lshlrev_b32_e32 v54, 16, v98
	v_and_b32_e32 v55, 0xffff0000, v98
	v_lshlrev_b32_e32 v56, 16, v99
	v_and_b32_e32 v57, 0xffff0000, v99
	v_pk_add_f32 v[52:53], v[52:53], v[56:57]
	v_pk_add_f32 v[50:51], v[50:51], v[54:55]
	v_add_f32_e32 v64, v64, v65
	v_mul_f32_e32 v54, v51, v51
	v_mul_f32_e32 v55, v53, v53
	v_add_f32_e32 v64, v108, v64
	v_add_f32_e32 v58, v58, v59
	v_fmac_f32_e32 v54, v50, v50
	v_fmac_f32_e32 v55, v52, v52
	v_add_f32_e32 v58, v64, v58
	v_add_f32_e32 v54, v54, v55
	v_add_f32_e32 v54, v58, v54
	v_cvt_pk_bf16_f32 v50, v50, v51
	v_cvt_pk_bf16_f32 v51, v52, v53
	v_mov_b32_e32 v198, v50
	v_mov_b32_e32 v199, v51
	s_nop 1
	v_permlane16_swap_b32_e32 v196, v198
	v_permlane16_swap_b32_e32 v197, v199
	global_store_dwordx4 v[62:63], v[196:199], off offset:256
	ds_bpermute_b32 v50, v114, v54
	s_waitcnt lgkmcnt(0)
	v_add_f32_e32 v50, v54, v50
	ds_bpermute_b32 v51, v115, v50
	s_and_saveexec_b64 s[80:81], s[6:7]
	s_cbranch_execz .LBB0_1049
	v_readlane_b32 s12, v253, 40
	v_lshlrev_b64 v[52:53], 6, v[96:97]
	v_readlane_b32 s13, v253, 41
	s_lshl_b32 s64, s90, 2
	s_waitcnt lgkmcnt(0)
	v_add_f32_e32 v50, v50, v51
	v_lshl_add_u64 v[52:53], s[12:13], 0, v[52:53]
	v_lshl_add_u64 v[52:53], s[78:79], 2, v[52:53]
	v_lshl_add_u64 v[52:53], v[52:53], 0, s[64:65]
	global_store_dword v[52:53], v50, off

; __device__ __forceinline__ unsigned cvt_pk_bf16(float lo, float hi) { unsigned r; asm volatile("v_cvt_pk_bf16_f32 %0, %1, %2" : "=v"(r) : "v"(lo), "v"(hi)); return r; }
;     __device__ __forceinline__ void operator()(f32x4 (&acc)[2][2][4][2], const Unit& u, int wr, int wc, int fr, int fq) const {
;     ...
;             for (int m = 0; m < 4; ++m) { const size_t off = (size_t)(u.pm * BM + ai * HALF + wr * 64 + m * 16 + fr) * ldc + col0;
; #pragma unroll
;                 for (int bj = 0; bj < 2; ++bj)
; #pragma unroll
;                     for (int n = 0; n < 2; ++n) old[m][bj][n] = *(const unsigned long long*)(xb + off + bj * HALF + n * 16); }
; #pragma unroll
;             for (int m = 0; m < 4; ++m) { const int row = u.pm * BM + ai * HALF + wr * 64 + m * 16 + fr; const size_t off = (size_t)row * ldc + col0; float sq = 0.f;
; #pragma unroll
;                 for (int bj = 0; bj < 2; ++bj)
; #pragma unroll
;                     for (int n = 0; n < 2; ++n) { const unsigned long long b = old[m][bj][n];
;                         const unsigned blo = (unsigned)b, bhi = (unsigned)(b >> 32);
;                         f32x4 v; v[0] = __builtin_bit_cast(float, blo << 16); v[1] = __builtin_bit_cast(float, blo & 0xffff0000u); v[2] = __builtin_bit_cast(float, bhi << 16); v[3] = __builtin_bit_cast(float, bhi & 0xffff0000u);
;                         v = v + acc[ai][bj][m][n];
;                         sq += (v[0] * v[0] + v[1] * v[1]) + (v[2] * v[2] + v[3] * v[3]);
;                         *(unsigned long long*)(xb + off + bj * HALF + n * 16) = (unsigned long long)cvt_pk_bf16(v[0], v[1]) | ((unsigned long long)cvt_pk_bf16(v[2], v[3]) << 32); }
;                 sq += __shfl_xor(sq, 16); sq += __shfl_xor(sq, 32);
;                 if (fq == 0) ssp[(size_t)row * 16 + 4 * u.pn + wc] = sq; }
.LBB0_1274:
	s_or_b64 exec, exec, s[78:79]
	v_add_u32_e32 v96, 0x80, v140
	v_ashrrev_i32_e32 v97, 31, v96
	v_lshlrev_b64 v[102:103], 11, v[96:97]
	s_waitcnt lgkmcnt(0)
	v_lshl_add_u64 v[66:67], v[138:139], 0, v[102:103]
	v_lshl_add_u64 v[66:67], v[66:67], 0, v[200:201]
	global_load_dwordx4 v[104:107], v[66:67], off
	global_load_dwordx4 v[98:101], v[66:67], off offset:256
	v_add_u32_e32 v84, 0x90, v140
	v_ashrrev_i32_e32 v85, 31, v84
	v_lshlrev_b64 v[66:67], 11, v[84:85]
	v_add_u32_e32 v70, 0xa0, v140
	v_lshl_add_u64 v[66:67], v[138:139], 0, v[66:67]
	v_ashrrev_i32_e32 v71, 31, v70
	v_lshl_add_u64 v[66:67], v[66:67], 0, v[200:201]
	global_load_dwordx4 v[88:91], v[66:67], off
	global_load_dwordx4 v[92:95], v[66:67], off offset:256
	v_lshlrev_b64 v[66:67], 11, v[70:71]
	v_lshl_add_u64 v[66:67], v[138:139], 0, v[66:67]
	v_lshl_add_u64 v[66:67], v[66:67], 0, v[200:201]
	global_load_dwordx4 v[72:75], v[66:67], off
	global_load_dwordx4 v[76:79], v[66:67], off offset:256
	v_add_u32_e32 v66, 0xb0, v140
	v_ashrrev_i32_e32 v67, 31, v66
	v_lshlrev_b64 v[68:69], 11, v[66:67]
	v_lshl_add_u64 v[68:69], v[138:139], 0, v[68:69]
	v_lshl_add_u64 v[68:69], v[68:69], 0, v[200:201]
	global_load_dwordx4 v[80:83], v[68:69], off
	s_nop 0
	global_load_dwordx4 v[202:205], v[68:69], off offset:256
	s_waitcnt vmcnt(0)
	v_permlane16_swap_b32_e32 v104, v106
	v_permlane16_swap_b32_e32 v105, v107
	v_permlane16_swap_b32_e32 v98, v100
	v_permlane16_swap_b32_e32 v99, v101
	v_permlane16_swap_b32_e32 v88, v90
	v_permlane16_swap_b32_e32 v89, v91
	v_permlane16_swap_b32_e32 v92, v94
	v_permlane16_swap_b32_e32 v93, v95
	v_permlane16_swap_b32_e32 v72, v74
	v_permlane16_swap_b32_e32 v73, v75
	v_permlane16_swap_b32_e32 v76, v78
	v_permlane16_swap_b32_e32 v77, v79
	v_permlane16_swap_b32_e32 v80, v82
	v_permlane16_swap_b32_e32 v81, v83
	v_permlane16_swap_b32_e32 v202, v204
	v_permlane16_swap_b32_e32 v203, v205
	v_mov_b32_e32 v86, v72
	v_mov_b32_e32 v87, v73
	v_mov_b32_e32 v72, v202
	v_mov_b32_e32 v73, v203
	v_mov_b32_e32 v68, v204
	v_mov_b32_e32 v69, v205
	v_mov_b32_e32 v209, v100
	v_mov_b32_e32 v100, v98
	v_mov_b32_e32 v98, v209
	v_mov_b32_e32 v208, v101
	v_mov_b32_e32 v101, v99
	v_mov_b32_e32 v99, v208
	v_mov_b32_e32 v207, v94
	v_mov_b32_e32 v94, v88
	v_mov_b32_e32 v88, v207
	v_mov_b32_e32 v206, v95
	v_mov_b32_e32 v95, v89
	v_mov_b32_e32 v89, v206
	v_mov_b32_e32 v199, v92
	v_mov_b32_e32 v92, v90
	v_mov_b32_e32 v90, v199
	v_mov_b32_e32 v198, v93
	v_mov_b32_e32 v93, v91
	v_mov_b32_e32 v91, v198
	v_mov_b32_e32 v197, v82
	v_mov_b32_e32 v82, v74
	v_mov_b32_e32 v74, v78
	v_mov_b32_e32 v78, v76
	v_mov_b32_e32 v76, v197
	v_mov_b32_e32 v196, v83
	v_mov_b32_e32 v83, v75
	v_mov_b32_e32 v75, v79
	v_mov_b32_e32 v79, v77
	v_mov_b32_e32 v77, v196
	v_lshlrev_b32_e32 v108, 16, v104
	v_and_b32_e32 v109, 0xffff0000, v104
	v_lshlrev_b32_e32 v104, 16, v105
	v_and_b32_e32 v105, 0xffff0000, v105
	v_pk_add_f32 v[64:65], v[64:65], v[104:105]
	v_pk_add_f32 v[62:63], v[62:63], v[108:109]
	v_mul_f32_e32 v105, v65, v65
	v_mul_f32_e32 v104, v63, v63
	v_fmac_f32_e32 v104, v62, v62
	v_fmac_f32_e32 v105, v64, v64
	v_add_f32_e32 v108, v104, v105
	v_cvt_pk_bf16_f32 v104, v62, v63
	v_cvt_pk_bf16_f32 v105, v64, v65
	s_waitcnt vmcnt(14)
	v_lshlrev_b32_e32 v64, 16, v106
	v_and_b32_e32 v65, 0xffff0000, v106
	v_lshl_add_u64 v[62:63], s[42:43], 0, v[102:103]
	v_pk_add_f32 v[58:59], v[58:59], v[64:65]
	v_lshl_add_u64 v[62:63], v[136:137], 1, v[62:63]
	v_lshlrev_b32_e32 v102, 16, v107
	v_and_b32_e32 v103, 0xffff0000, v107
	v_mul_f32_e32 v64, v59, v59
	v_lshl_add_u64 v[62:63], v[62:63], 0, v[200:201]
	v_mov_b32_e32 v192, v104
	v_mov_b32_e32 v193, v105
	v_pk_add_f32 v[60:61], v[60:61], v[102:103]
	v_fmac_f32_e32 v64, v58, v58
	v_cvt_pk_bf16_f32 v58, v58, v59
	v_cvt_pk_bf16_f32 v59, v60, v61
	v_mul_f32_e32 v65, v61, v61
	v_mov_b32_e32 v194, v58
	v_mov_b32_e32 v195, v59
	s_nop 1
	v_permlane16_swap_b32_e32 v192, v194
	v_permlane16_swap_b32_e32 v193, v195
	global_store_dwordx4 v[62:63], v[192:195], off
	s_waitcnt vmcnt(14)
	v_lshlrev_b32_e32 v58, 16, v100
	v_and_b32_e32 v59, 0xffff0000, v100
	v_fmac_f32_e32 v65, v60, v60
	v_lshlrev_b32_e32 v60, 16, v101
	v_and_b32_e32 v61, 0xffff0000, v101
	v_pk_add_f32 v[54:55], v[54:55], v[58:59]
	v_pk_add_f32 v[56:57], v[56:57], v[60:61]
	v_mul_f32_e32 v58, v55, v55
	v_fmac_f32_e32 v58, v54, v54
	v_mul_f32_e32 v59, v57, v57
	v_cvt_pk_bf16_f32 v54, v54, v55
	v_cvt_pk_bf16_f32 v55, v56, v57
	v_fmac_f32_e32 v59, v56, v56
	v_mov_b32_e32 v196, v54
	v_mov_b32_e32 v197, v55
	s_waitcnt vmcnt(13)
	v_lshlrev_b32_e32 v54, 16, v98
	v_and_b32_e32 v55, 0xffff0000, v98
	v_lshlrev_b32_e32 v56, 16, v99
	v_and_b32_e32 v57, 0xffff0000, v99
	v_pk_add_f32 v[52:53], v[52:53], v[56:57]
	v_pk_add_f32 v[50:51], v[50:51], v[54:55]
	v_add_f32_e32 v64, v64, v65
	v_mul_f32_e32 v54, v51, v51
	v_mul_f32_e32 v55, v53, v53
	v_add_f32_e32 v64, v108, v64
	v_add_f32_e32 v58, v58, v59
	v_fmac_f32_e32 v54, v50, v50
	v_fmac_f32_e32 v55, v52, v52
	v_add_f32_e32 v58, v64, v58
	v_add_f32_e32 v54, v54, v55
	v_add_f32_e32 v54, v58, v54
	v_cvt_pk_bf16_f32 v50, v50, v51
	v_cvt_pk_bf16_f32 v51, v52, v53
	v_mov_b32_e32 v198, v50
	v_mov_b32_e32 v199, v51
	s_nop 1
	v_permlane16_swap_b32_e32 v196, v198
	v_permlane16_swap_b32_e32 v197, v199
	global_store_dwordx4 v[62:63], v[196:199], off offset:256
	ds_bpermute_b32 v50, v114, v54
	s_waitcnt lgkmcnt(0)
	v_add_f32_e32 v50, v54, v50
	ds_bpermute_b32 v51, v115, v50
	s_and_saveexec_b64 s[78:79], s[6:7]
	s_cbranch_execz .LBB0_1276
	v_lshlrev_b64 v[52:53], 6, v[96:97]
	v_lshl_add_u64 v[52:53], s[14:15], 0, v[52:53]
	v_lshl_add_u64 v[52:53], s[76:77], 2, v[52:53]
	s_lshl_b32 s64, s86, 2
	v_lshl_add_u64 v[52:53], v[52:53], 0, s[64:65]
	s_waitcnt lgkmcnt(0)
	v_add_f32_e32 v50, v50, v51
	global_store_dword v[52:53], v50, off

; __device__ __forceinline__ unsigned cvt_pk_bf16(float lo, float hi) { unsigned r; asm volatile("v_cvt_pk_bf16_f32 %0, %1, %2" : "=v"(r) : "v"(lo), "v"(hi)); return r; }
;     __device__ __forceinline__ void operator()(f32x4 (&acc)[2][2][4][2], const Unit& u, int wr, int wc, int fr, int fq) const {
;     ...
;             for (int m = 0; m < 4; ++m) { const size_t off = (size_t)(u.pm * BM + ai * HALF + wr * 64 + m * 16 + fr) * ldc + col0;
; #pragma unroll
;                 for (int bj = 0; bj < 2; ++bj)
; #pragma unroll
;                     for (int n = 0; n < 2; ++n) old[m][bj][n] = *(const unsigned long long*)(xb + off + bj * HALF + n * 16); }
; #pragma unroll
;             for (int m = 0; m < 4; ++m) { const int row = u.pm * BM + ai * HALF + wr * 64 + m * 16 + fr; const size_t off = (size_t)row * ldc + col0; float sq = 0.f;
; #pragma unroll
;                 for (int bj = 0; bj < 2; ++bj)
; #pragma unroll
;                     for (int n = 0; n < 2; ++n) { const unsigned long long b = old[m][bj][n];
;                         const unsigned blo = (unsigned)b, bhi = (unsigned)(b >> 32);
;                         f32x4 v; v[0] = __builtin_bit_cast(float, blo << 16); v[1] = __builtin_bit_cast(float, blo & 0xffff0000u); v[2] = __builtin_bit_cast(float, bhi << 16); v[3] = __builtin_bit_cast(float, bhi & 0xffff0000u);
;                         v = v + acc[ai][bj][m][n];
;                         sq += (v[0] * v[0] + v[1] * v[1]) + (v[2] * v[2] + v[3] * v[3]);
;                         *(unsigned long long*)(xb + off + bj * HALF + n * 16) = (unsigned long long)cvt_pk_bf16(v[0], v[1]) | ((unsigned long long)cvt_pk_bf16(v[2], v[3]) << 32); }
;                 sq += __shfl_xor(sq, 16); sq += __shfl_xor(sq, 32);
;                 if (fq == 0) ssp[(size_t)row * 16 + 4 * u.pn + wc] = sq; }
.LBB0_1523:
	s_or_b64 exec, exec, s[74:75]
	v_add_u32_e32 v96, 0x80, v140
	v_ashrrev_i32_e32 v97, 31, v96
	v_lshlrev_b64 v[102:103], 11, v[96:97]
	s_waitcnt lgkmcnt(0)
	v_lshl_add_u64 v[66:67], v[138:139], 0, v[102:103]
	v_lshl_add_u64 v[66:67], v[66:67], 0, v[200:201]
	global_load_dwordx4 v[104:107], v[66:67], off
	global_load_dwordx4 v[98:101], v[66:67], off offset:256
	v_add_u32_e32 v84, 0x90, v140
	v_ashrrev_i32_e32 v85, 31, v84
	v_lshlrev_b64 v[66:67], 11, v[84:85]
	v_add_u32_e32 v70, 0xa0, v140
	v_lshl_add_u64 v[66:67], v[138:139], 0, v[66:67]
	v_ashrrev_i32_e32 v71, 31, v70
	v_lshl_add_u64 v[66:67], v[66:67], 0, v[200:201]
	global_load_dwordx4 v[88:91], v[66:67], off
	global_load_dwordx4 v[92:95], v[66:67], off offset:256
	v_lshlrev_b64 v[66:67], 11, v[70:71]
	v_lshl_add_u64 v[66:67], v[138:139], 0, v[66:67]
	v_lshl_add_u64 v[66:67], v[66:67], 0, v[200:201]
	global_load_dwordx4 v[72:75], v[66:67], off
	global_load_dwordx4 v[76:79], v[66:67], off offset:256
	v_add_u32_e32 v66, 0xb0, v140
	v_ashrrev_i32_e32 v67, 31, v66
	v_lshlrev_b64 v[68:69], 11, v[66:67]
	v_lshl_add_u64 v[68:69], v[138:139], 0, v[68:69]
	v_lshl_add_u64 v[68:69], v[68:69], 0, v[200:201]
	global_load_dwordx4 v[80:83], v[68:69], off
	s_nop 0
	global_load_dwordx4 v[202:205], v[68:69], off offset:256
	s_waitcnt vmcnt(0)
	v_permlane16_swap_b32_e32 v104, v106
	v_permlane16_swap_b32_e32 v105, v107
	v_permlane16_swap_b32_e32 v98, v100
	v_permlane16_swap_b32_e32 v99, v101
	v_permlane16_swap_b32_e32 v88, v90
	v_permlane16_swap_b32_e32 v89, v91
	v_permlane16_swap_b32_e32 v92, v94
	v_permlane16_swap_b32_e32 v93, v95
	v_permlane16_swap_b32_e32 v72, v74
	v_permlane16_swap_b32_e32 v73, v75
	v_permlane16_swap_b32_e32 v76, v78
	v_permlane16_swap_b32_e32 v77, v79
	v_permlane16_swap_b32_e32 v80, v82
	v_permlane16_swap_b32_e32 v81, v83
	v_permlane16_swap_b32_e32 v202, v204
	v_permlane16_swap_b32_e32 v203, v205
	v_mov_b32_e32 v86, v72
	v_mov_b32_e32 v87, v73
	v_mov_b32_e32 v72, v202
	v_mov_b32_e32 v73, v203
	v_mov_b32_e32 v68, v204
	v_mov_b32_e32 v69, v205
	v_mov_b32_e32 v209, v100
	v_mov_b32_e32 v100, v98
	v_mov_b32_e32 v98, v209
	v_mov_b32_e32 v208, v101
	v_mov_b32_e32 v101, v99
	v_mov_b32_e32 v99, v208
	v_mov_b32_e32 v207, v94
	v_mov_b32_e32 v94, v88
	v_mov_b32_e32 v88, v207
	v_mov_b32_e32 v206, v95
	v_mov_b32_e32 v95, v89
	v_mov_b32_e32 v89, v206
	v_mov_b32_e32 v199, v92
	v_mov_b32_e32 v92, v90
	v_mov_b32_e32 v90, v199
	v_mov_b32_e32 v198, v93
	v_mov_b32_e32 v93, v91
	v_mov_b32_e32 v91, v198
	v_mov_b32_e32 v197, v82
	v_mov_b32_e32 v82, v74
	v_mov_b32_e32 v74, v78
	v_mov_b32_e32 v78, v76
	v_mov_b32_e32 v76, v197
	v_mov_b32_e32 v196, v83
	v_mov_b32_e32 v83, v75
	v_mov_b32_e32 v75, v79
	v_mov_b32_e32 v79, v77
	v_mov_b32_e32 v77, v196
	v_lshlrev_b32_e32 v108, 16, v104
	v_and_b32_e32 v109, 0xffff0000, v104
	v_lshlrev_b32_e32 v104, 16, v105
	v_and_b32_e32 v105, 0xffff0000, v105
	v_pk_add_f32 v[64:65], v[64:65], v[104:105]
	v_pk_add_f32 v[62:63], v[62:63], v[108:109]
	v_mul_f32_e32 v105, v65, v65
	v_mul_f32_e32 v104, v63, v63
	v_fmac_f32_e32 v104, v62, v62
	v_fmac_f32_e32 v105, v64, v64
	v_add_f32_e32 v108, v104, v105
	v_cvt_pk_bf16_f32 v104, v62, v63
	v_cvt_pk_bf16_f32 v105, v64, v65
	s_waitcnt vmcnt(14)
	v_lshlrev_b32_e32 v64, 16, v106
	v_and_b32_e32 v65, 0xffff0000, v106
	v_lshl_add_u64 v[62:63], s[42:43], 0, v[102:103]
	v_pk_add_f32 v[58:59], v[58:59], v[64:65]
	v_lshl_add_u64 v[62:63], v[136:137], 1, v[62:63]
	v_lshlrev_b32_e32 v102, 16, v107
	v_and_b32_e32 v103, 0xffff0000, v107
	v_mul_f32_e32 v64, v59, v59
	v_lshl_add_u64 v[62:63], v[62:63], 0, v[200:201]
	v_mov_b32_e32 v192, v104
	v_mov_b32_e32 v193, v105
	v_pk_add_f32 v[60:61], v[60:61], v[102:103]
	v_fmac_f32_e32 v64, v58, v58
	v_cvt_pk_bf16_f32 v58, v58, v59
	v_cvt_pk_bf16_f32 v59, v60, v61
	v_mul_f32_e32 v65, v61, v61
	v_mov_b32_e32 v194, v58
	v_mov_b32_e32 v195, v59
	s_nop 1
	v_permlane16_swap_b32_e32 v192, v194
	v_permlane16_swap_b32_e32 v193, v195
	global_store_dwordx4 v[62:63], v[192:195], off
	s_waitcnt vmcnt(14)
	v_lshlrev_b32_e32 v58, 16, v100
	v_and_b32_e32 v59, 0xffff0000, v100
	v_fmac_f32_e32 v65, v60, v60
	v_lshlrev_b32_e32 v60, 16, v101
	v_and_b32_e32 v61, 0xffff0000, v101
	v_pk_add_f32 v[54:55], v[54:55], v[58:59]
	v_pk_add_f32 v[56:57], v[56:57], v[60:61]
	v_mul_f32_e32 v58, v55, v55
	v_fmac_f32_e32 v58, v54, v54
	v_mul_f32_e32 v59, v57, v57
	v_cvt_pk_bf16_f32 v54, v54, v55
	v_cvt_pk_bf16_f32 v55, v56, v57
	v_fmac_f32_e32 v59, v56, v56
	v_mov_b32_e32 v196, v54
	v_mov_b32_e32 v197, v55
	s_waitcnt vmcnt(13)
	v_lshlrev_b32_e32 v54, 16, v98
	v_and_b32_e32 v55, 0xffff0000, v98
	v_lshlrev_b32_e32 v56, 16, v99
	v_and_b32_e32 v57, 0xffff0000, v99
	v_pk_add_f32 v[52:53], v[52:53], v[56:57]
	v_pk_add_f32 v[50:51], v[50:51], v[54:55]
	v_add_f32_e32 v64, v64, v65
	v_mul_f32_e32 v54, v51, v51
	v_mul_f32_e32 v55, v53, v53
	v_add_f32_e32 v64, v108, v64
	v_add_f32_e32 v58, v58, v59
	v_fmac_f32_e32 v54, v50, v50
	v_fmac_f32_e32 v55, v52, v52
	v_add_f32_e32 v58, v64, v58
	v_add_f32_e32 v54, v54, v55
	v_add_f32_e32 v54, v58, v54
	v_cvt_pk_bf16_f32 v50, v50, v51
	v_cvt_pk_bf16_f32 v51, v52, v53
	v_mov_b32_e32 v198, v50
	v_mov_b32_e32 v199, v51
	s_nop 1
	v_permlane16_swap_b32_e32 v196, v198
	v_permlane16_swap_b32_e32 v197, v199
	global_store_dwordx4 v[62:63], v[196:199], off offset:256
	ds_bpermute_b32 v50, v114, v54
	s_waitcnt lgkmcnt(0)
	v_add_f32_e32 v50, v54, v50
	ds_bpermute_b32 v51, v115, v50
	s_and_saveexec_b64 s[74:75], s[4:5]
	s_cbranch_execz .LBB0_1525
	v_readlane_b32 s12, v253, 38
	v_lshlrev_b64 v[52:53], 6, v[96:97]
	v_readlane_b32 s13, v253, 39
	s_lshl_b32 s64, s82, 2
	s_waitcnt lgkmcnt(0)
	v_add_f32_e32 v50, v50, v51
	v_lshl_add_u64 v[52:53], s[12:13], 0, v[52:53]
	v_lshl_add_u64 v[52:53], s[72:73], 2, v[52:53]
	v_lshl_add_u64 v[52:53], v[52:53], 0, s[64:65]
	global_store_dword v[52:53], v50, off
